# context attention unit: Q fragments and first K/V tile prefetched at the end of the neighbourhood loop into idle registers
# baseline (speedup 1.0000x reference)
.LBB0_625:
	v_mov_b32_e32 v0, v224
	s_nop 1
	v_permlane32_swap_b32_e32 v224, v0
	v_add_f32_e32 v0, v224, v0
	s_waitcnt vmcnt(0)
	global_load_dwordx4 v[64:67], v[142:143], off offset:1024
	global_load_dwordx4 v[68:71], v[142:143], off offset:1056
	global_load_dwordx4 v[72:75], v[142:143], off offset:1088
	global_load_dwordx4 v[76:79], v[142:143], off offset:1120
	global_load_dwordx4 v[116:119], v[142:143], off offset:1152
	global_load_dwordx4 v[120:123], v[142:143], off offset:1184
	global_load_dwordx4 v[124:127], v[142:143], off offset:1216
	global_load_dwordx4 v[128:131], v[142:143], off offset:1248
	v_readlane_b32 s24, v253, 45
	v_readlane_b32 s25, v253, 46
	s_lshl_b64 s[24:25], s[24:25], 20
	s_lshl_b32 s14, s16, 5
	s_ashr_i32 s15, s14, 31
	v_lshl_add_u64 v[50:51], v[134:135], 0, s[14:15]
	v_lshlrev_b64 v[50:51], 7, v[50:51]
	v_lshl_add_u64 v[50:51], v[136:137], 0, v[50:51]
	s_and_b32 s14, s14, 0xffffff00
	s_ashr_i32 s15, s14, 31
	s_lshl_b64 s[14:15], s[14:15], 6
	s_add_u32 s14, s14, s24
	s_addc_u32 s15, s15, s25
	s_lshl_b64 s[14:15], s[14:15], 1
	v_lshl_add_u64 v[112:113], v[138:139], 0, s[14:15]
	v_lshl_add_u64 v[88:89], v[140:141], 0, s[14:15]
	global_load_dwordx4 v[56:59], v[50:51], off
	global_load_dwordx4 v[60:63], v[50:51], off offset:32
	global_load_dwordx4 v[96:99], v[50:51], off offset:64
	global_load_dwordx4 v[50:53], v[50:51], off offset:96
	global_load_dwordx4 v[104:107], v[112:113], off
	global_load_dwordx4 v[100:103], v[112:113], off offset:1024
	global_load_dwordx4 v[108:111], v[112:113], off offset:2048
	global_load_dwordx4 v[112:115], v[112:113], off offset:3072
	global_load_dwordx4 v[92:95], v[88:89], off
	global_load_dwordx4 v[80:83], v[88:89], off offset:1024
	global_load_dwordx4 v[84:87], v[88:89], off offset:2048
	global_load_dwordx4 v[88:91], v[88:89], off offset:3072
	v_div_scale_f32 v2, s[12:13], v0, v0, 1.0
	v_rcp_f32_e32 v3, v2
	s_nop 0
	v_fma_f32 v4, -v2, v3, 1.0
	v_fmac_f32_e32 v3, v4, v3
	v_div_scale_f32 v4, vcc, 1.0, v0, 1.0
	v_mul_f32_e32 v5, v4, v3
	v_fma_f32 v6, -v2, v5, v4
	v_fmac_f32_e32 v5, v6, v3
	v_fma_f32 v2, -v2, v5, v4
	v_div_fmas_f32 v2, v2, v3, v5
	v_div_fixup_f32 v0, v2, v0, 1.0
	v_pk_mul_f32 v[8:9], v[16:17], v[0:1] op_sel_hi:[1,0]
	v_pk_mul_f32 v[48:49], v[32:33], v[0:1] op_sel_hi:[1,0]
	v_pk_mul_f32 v[2:3], v[8:9], v[8:9]
	v_pk_mul_f32 v[10:11], v[18:19], v[0:1] op_sel_hi:[1,0]
	v_pk_fma_f32 v[2:3], v[48:49], v[48:49], v[2:3]
	v_pk_mul_f32 v[34:35], v[34:35], v[0:1] op_sel_hi:[1,0]
	v_pk_mul_f32 v[4:5], v[10:11], v[10:11]
	v_pk_add_f32 v[2:3], v[2:3], v[2:3] op_sel:[0,1] op_sel_hi:[1,0]
	v_pk_fma_f32 v[4:5], v[34:35], v[34:35], v[4:5]
	v_pk_mul_f32 v[18:19], v[36:37], v[0:1] op_sel_hi:[1,0]
	v_pk_add_f32 v[2:3], v[4:5], v[2:3]
	v_pk_mul_f32 v[12:13], v[22:23], v[0:1] op_sel_hi:[1,0]
	v_pk_add_f32 v[4:5], v[4:5], v[2:3] op_sel:[1,0] op_sel_hi:[0,1]
	v_pk_mul_f32 v[2:3], v[20:21], v[0:1] op_sel_hi:[1,0]
	v_pk_mul_f32 v[32:33], v[38:39], v[0:1] op_sel_hi:[1,0]
	v_pk_mul_f32 v[6:7], v[2:3], v[2:3]
	v_pk_mul_f32 v[20:21], v[40:41], v[0:1] op_sel_hi:[1,0]
	v_pk_fma_f32 v[6:7], v[18:19], v[18:19], v[6:7]
	v_pk_mul_f32 v[22:23], v[44:45], v[0:1] op_sel_hi:[1,0]
	v_pk_add_f32 v[4:5], v[6:7], v[4:5]
	s_nop 0
	v_pk_add_f32 v[4:5], v[6:7], v[4:5] op_sel:[1,0] op_sel_hi:[0,1]
	v_pk_mul_f32 v[6:7], v[12:13], v[12:13]
	s_nop 0
	v_pk_fma_f32 v[6:7], v[32:33], v[32:33], v[6:7]
	s_nop 0
	v_pk_add_f32 v[4:5], v[6:7], v[4:5]
	s_nop 0
	v_pk_add_f32 v[6:7], v[6:7], v[4:5] op_sel:[1,0] op_sel_hi:[0,1]
	v_pk_mul_f32 v[4:5], v[24:25], v[0:1] op_sel_hi:[1,0]
	v_pk_mul_f32 v[24:25], v[42:43], v[0:1] op_sel_hi:[1,0]
	v_pk_mul_f32 v[14:15], v[4:5], v[4:5]
	s_nop 0
	v_pk_fma_f32 v[14:15], v[20:21], v[20:21], v[14:15]
	s_nop 0
	v_pk_add_f32 v[6:7], v[14:15], v[6:7]
	s_nop 0
	v_pk_add_f32 v[6:7], v[14:15], v[6:7] op_sel:[1,0] op_sel_hi:[0,1]
	v_pk_mul_f32 v[14:15], v[26:27], v[0:1] op_sel_hi:[1,0]
	s_nop 0
	v_pk_mul_f32 v[16:17], v[14:15], v[14:15]
	s_nop 0
	v_pk_fma_f32 v[16:17], v[24:25], v[24:25], v[16:17]
	s_nop 0
	v_pk_add_f32 v[6:7], v[16:17], v[6:7]
	s_nop 0
	v_pk_add_f32 v[16:17], v[16:17], v[6:7] op_sel:[1,0] op_sel_hi:[0,1]
	v_pk_mul_f32 v[6:7], v[28:29], v[0:1] op_sel_hi:[1,0]
	s_nop 0
	v_pk_mul_f32 v[26:27], v[6:7], v[6:7]
	s_nop 0
	v_pk_fma_f32 v[26:27], v[22:23], v[22:23], v[26:27]
	s_nop 0
	v_pk_add_f32 v[16:17], v[26:27], v[16:17]
	s_nop 0
	v_pk_add_f32 v[28:29], v[26:27], v[16:17] op_sel:[1,0] op_sel_hi:[0,1]
	v_pk_mul_f32 v[16:17], v[30:31], v[0:1] op_sel_hi:[1,0]
	v_pk_mul_f32 v[26:27], v[46:47], v[0:1] op_sel_hi:[1,0]
	v_pk_mul_f32 v[30:31], v[16:17], v[16:17]
	s_nop 0
	v_pk_fma_f32 v[30:31], v[26:27], v[26:27], v[30:31]
	s_nop 0
	v_pk_add_f32 v[28:29], v[30:31], v[28:29]
	s_nop 0
	v_pk_add_f32 v[28:29], v[30:31], v[28:29] op_sel:[1,0] op_sel_hi:[0,1]
	v_mov_b32_e32 v0, v28
	s_nop 1
	v_permlane32_swap_b32_e32 v28, v0
	s_and_saveexec_b64 s[12:13], s[4:5]
	s_cbranch_execz .LBB0_606
	v_add_f32_e32 v0, v28, v0
	ds_write_b32 v133, v0 offset:61440
	s_branch .LBB0_606
.LBB0_627:
	v_readlane_b32 s6, v253, 45
	s_mov_b64 s[8:9], 0xb801800
	v_readlane_b32 s7, v253, 46
	v_lshl_add_u64 v[146:147], v[160:161], 0, s[8:9]
	s_mov_b64 s[8:9], 0xa801800
	s_lshl_b64 s[6:7], s[6:7], 20
	v_lshl_add_u64 v[148:149], v[158:159], 0, s[8:9]
	s_mov_b32 s12, 1
	s_branch .LBB0_629

.LBB0_629:
	s_and_b32 s8, s17, 0xffffff00
	s_ashr_i32 s9, s8, 31
	s_lshl_b64 s[8:9], s[8:9], 7
	v_lshl_add_u64 v[150:151], v[146:147], 0, s[8:9]
	v_lshl_add_u64 v[152:153], v[148:149], 0, s[8:9]
	s_lshl_b32 s8, s16, 5
	s_and_b32 s10, s8, 0xffffff00
	s_ashr_i32 s11, s10, 31
	s_ashr_i32 s9, s8, 31
	s_lshl_b64 s[10:11], s[10:11], 6
	s_add_u32 s10, s10, s6
	v_lshl_add_u64 v[2:3], v[134:135], 0, s[8:9]
	s_addc_u32 s11, s11, s7
	v_lshlrev_b64 v[2:3], 7, v[2:3]
	s_lshl_b64 s[10:11], s[10:11], 1
	v_lshl_add_u64 v[2:3], v[136:137], 0, v[2:3]
	v_lshl_add_u64 v[154:155], v[138:139], 0, s[10:11]
	v_lshl_add_u64 v[156:157], v[140:141], 0, s[10:11]
	s_cmp_eq_u32 s12, 1
	s_cbranch_scc1 .Lctx_pref
	global_load_dwordx4 v[64:67], v[2:3], off
	global_load_dwordx4 v[68:71], v[2:3], off offset:32
	global_load_dwordx4 v[72:75], v[2:3], off offset:64
	global_load_dwordx4 v[76:79], v[2:3], off offset:96
	global_load_dwordx4 v[104:107], v[154:155], off
	global_load_dwordx4 v[100:103], v[154:155], off offset:1024
	global_load_dwordx4 v[108:111], v[154:155], off offset:2048
	global_load_dwordx4 v[112:115], v[154:155], off offset:3072
	global_load_dwordx4 v[92:95], v[156:157], off
	global_load_dwordx4 v[80:83], v[156:157], off offset:1024
	global_load_dwordx4 v[84:87], v[156:157], off offset:2048
	global_load_dwordx4 v[88:91], v[156:157], off offset:3072
	s_branch .Lctx_go
.Lctx_pref:
	v_mov_b64_e32 v[64:65], v[56:57]
	v_mov_b64_e32 v[66:67], v[58:59]
	v_mov_b64_e32 v[68:69], v[60:61]
	v_mov_b64_e32 v[70:71], v[62:63]
	v_mov_b64_e32 v[72:73], v[96:97]
	v_mov_b64_e32 v[74:75], v[98:99]
	v_mov_b64_e32 v[76:77], v[50:51]
	v_mov_b64_e32 v[78:79], v[52:53]
.Lctx_go:
	v_mov_b32_e32 v14, v1
	v_mov_b32_e32 v15, v1
	v_mov_b32_e32 v0, v1
	v_mov_b32_e32 v2, v1
	v_mov_b32_e32 v3, v1
	v_mov_b32_e32 v4, v1
	v_mov_b32_e32 v5, v1
	v_mov_b32_e32 v6, v1
	v_mov_b32_e32 v7, v1
	v_mov_b32_e32 v8, v1
	v_mov_b32_e32 v9, v1
	v_mov_b32_e32 v10, v1
	v_mov_b32_e32 v11, v1
	v_mov_b32_e32 v12, v1
	v_mov_b32_e32 v13, v1
	v_mov_b64_e32 v[30:31], v[14:15]
	v_mov_b64_e32 v[46:47], v[14:15]
	s_mov_b32 s9, 0
	v_mov_b32_e32 v159, 0
	v_mov_b32_e32 v158, 0xf149f2ca
	s_movk_i32 s12, 0x1000
	v_mov_b64_e32 v[28:29], v[12:13]
	v_mov_b64_e32 v[26:27], v[10:11]
	v_mov_b64_e32 v[24:25], v[8:9]
	v_mov_b64_e32 v[22:23], v[6:7]
	v_mov_b64_e32 v[20:21], v[4:5]
	v_mov_b64_e32 v[18:19], v[2:3]
	v_mov_b64_e32 v[16:17], v[0:1]
	v_mov_b64_e32 v[44:45], v[12:13]
	v_mov_b64_e32 v[42:43], v[10:11]
	v_mov_b64_e32 v[40:41], v[8:9]
	v_mov_b64_e32 v[38:39], v[6:7]
	v_mov_b64_e32 v[36:37], v[4:5]
	v_mov_b64_e32 v[34:35], v[2:3]
	v_mov_b64_e32 v[32:33], v[0:1]
	s_branch .LBB0_631
